# adds: work-queue ticket prefetched during prompt attention units (atomic latency hidden)
# baseline (speedup 1.0000x reference)
; __global__ void __launch_bounds__(512, 2) fwd_megakernel(Params P) {
;     ...
;             unsigned* cnt = (unsigned*)(ws + WS_CTL) + li;
;             constexpr int T_HP = 32 * NSEG, T_AP = T_HP + 2048, T_AS = T_AP + 128, T_HSM = T_AS + 64, T_SO = T_HSM + 16, T_FX = T_SO + 32 * NSEG;
;             unsigned* segdone = (unsigned*)(ws + WS_CTL) + 32 + 32 * li;
;             for (;;) {
.LBB0_534:
	s_or_b64 exec, exec, s[12:13]
	s_lshl_b32 s6, s14, 5
	s_mov_b32 s7, s95
	s_mov_b32 s8, s6
	v_writelane_b32 v242, s8, 2
	s_lshl_b64 s[6:7], s[6:7], 2
	s_add_u32 s3, s88, s6
	v_writelane_b32 v242, s9, 3
	v_writelane_b32 v242, s3, 4
	s_addc_u32 s3, s89, s7
	s_lshl_b32 s94, s14, 2
	s_lshl_b64 s[6:7], s[94:95], 2
	s_add_u32 s6, s88, s6
	v_writelane_b32 v242, s3, 5
	s_addc_u32 s7, s89, s7
	v_writelane_b32 v242, s6, 6
	s_mul_i32 s3, s14, 0x18400
	v_readlane_b32 s40, v245, 0
	v_writelane_b32 v242, s7, 7
	v_writelane_b32 v242, s3, 8
	s_add_u32 s3, s3, 0x10000
	v_writelane_b32 v242, s3, 9
	s_addc_u32 s3, 0, 0
	v_writelane_b32 v242, s3, 10
	s_mul_i32 s3, s14, 0x610
	v_writelane_b32 v242, s3, 11
	s_add_u32 s3, s3, 0x400
	v_writelane_b32 v242, s3, 12
	s_addc_u32 s3, 0, 0
	s_lshl_b32 s94, s14, 9
	v_writelane_b32 v242, s3, 13
	s_lshl_b32 s3, s14, 4
	s_lshl_b64 s[6:7], s[94:95], 2
	v_readlane_b32 s44, v245, 4
	v_writelane_b32 v242, s3, 14
	v_readlane_b32 s45, v245, 5
	s_add_u32 s3, s44, s6
	v_writelane_b32 v242, s3, 15
	s_addc_u32 s3, s45, s7
	v_writelane_b32 v242, s3, 16
	v_readlane_b32 s3, v245, 26
	s_add_u32 s20, s3, s58
	v_readlane_b32 s3, v245, 27
	s_addc_u32 s21, s3, s59
	v_readlane_b32 s3, v243, 45
	s_add_u32 s3, s3, s58
	s_mov_b64 s[74:75], 0
	v_writelane_b32 v242, s3, 17
	v_readlane_b32 s3, v243, 46
	s_addc_u32 s3, s3, s59
	v_readlane_b32 s41, v245, 1
	v_writelane_b32 v242, s3, 18
	v_writelane_b32 v242, s20, 19
	v_readlane_b32 s42, v245, 2
	v_readlane_b32 s43, v245, 3
	v_readlane_b32 s46, v245, 6
	v_readlane_b32 s47, v245, 7
	v_writelane_b32 v242, s21, 20
	s_mov_b32 s100, 0
	s_branch .LBB0_542

; __global__ void __launch_bounds__(512, 2) fwd_megakernel(Params P) {
;     ...
;             for (;;) {
;                 if (tid == 0) *slot = (int)atomicAdd(cnt, 1u);
;                 __syncthreads();
;                 const int pt = *slot;
;                 __syncthreads();
.LBB0_542:
	s_and_saveexec_b64 s[22:23], s[68:69]
	s_cbranch_execz .LBB0_546
	s_mov_b64 s[40:41], exec
	v_mbcnt_lo_u32_b32 v0, s40, 0
	v_mbcnt_hi_u32_b32 v0, s41, v0
	v_cmp_eq_u32_e32 vcc, 0, v0
	s_and_saveexec_b64 s[38:39], vcc
	s_cbranch_execz .LBB0_545
	s_bcnt1_i32_b64 s5, s[40:41]
	v_mov_b32_e32 v2, s5
	s_cmp_eq_u32 s100, 0
	s_cbranch_scc1 .Ltk_sync
	s_waitcnt vmcnt(0)
	v_mov_b32_e32 v2, v246
	s_branch .LBB0_545
.Ltk_sync:
	global_atomic_add v2, v1, v2, s[0:1] sc0

; __global__ void __launch_bounds__(512, 2) fwd_megakernel(Params P) {
;     ...
;                 if (pt >= T_FX) break;
;                 int tk;
;                 { constexpr int A1 = 1408, P1_ = T_HP + A1, P2_ = P1_ + 32 * NSEG, P3_ = P2_ + 128, P4_ = P3_ + 64, P5_ = P4_ + 16;
;                   if (pt < P1_) tk = pt;
;                   else if (pt < P2_) tk = T_SO + (pt - P1_);
;                   else if (pt < P3_) tk = T_AP + (pt - P2_);
;                   else if (pt < P4_) tk = T_AS + (pt - P3_);
;                   else if (pt < P5_) tk = T_HSM + (pt - P4_);
;                   else tk = T_HP + A1 + (pt - P5_); }
.LBB0_546:
	s_or_b64 exec, exec, s[22:23]
	v_readlane_b32 s3, v243, 49
	s_waitcnt lgkmcnt(0)
	s_barrier
	v_mov_b32_e32 v0, s3
	ds_read_b32 v0, v0
	s_movk_i32 s5, 0xacf
	s_waitcnt lgkmcnt(0)
	s_barrier
	v_cmp_lt_i32_e64 s[38:39], s5, v0
	v_readfirstlane_b32 s7, v0
	s_and_b64 vcc, exec, s[38:39]
	s_cbranch_vccnz .LBB0_541
	s_mov_b32 s100, 0
	s_cmpk_lt_i32 s7, 0x100
	s_cbranch_scc1 .Ltk_nopf
	s_cmpk_lt_i32 s7, 0x680
	s_cbranch_scc1 .Ltk_pf
	s_cmpk_lt_i32 s7, 0x850
	s_cbranch_scc1 .Ltk_nopf
.Ltk_pf:
	s_mov_b32 s100, 1
	s_and_saveexec_b64 s[98:99], s[68:69]
	s_cbranch_execz .Ltk_pf_done
	v_mov_b32_e32 v246, 1
	global_atomic_add v246, v1, v246, s[0:1] sc0
.Ltk_pf_done:
	s_or_b64 exec, exec, s[98:99]
.Ltk_nopf:
	s_cmpk_lt_i32 s7, 0x680
	s_cbranch_scc1 .LBB0_565
	s_cmpk_gt_u32 s7, 0x77f
	s_mov_b64 s[22:23], -1
	s_cbranch_scc0 .LBB0_562
	s_cmpk_gt_u32 s7, 0x7ff
	s_cbranch_scc0 .LBB0_559
	s_cmpk_gt_u32 s7, 0x83f
	s_cbranch_scc0 .LBB0_556
	s_cmpk_gt_u32 s7, 0x84f
	s_cbranch_scc0 .LBB0_553
	s_add_i32 s5, s7, 0xfffffe30
	s_mov_b64 s[22:23], 0

; __global__ void __launch_bounds__(512, 2) fwd_megakernel(Params P) {
	.amdhsa_kernel _Z14fwd_megakernel6Params
		.amdhsa_group_segment_fixed_size 0
		.amdhsa_private_segment_fixed_size 0
		.amdhsa_kernarg_size 376
		.amdhsa_user_sgpr_count 2
		.amdhsa_user_sgpr_dispatch_ptr 0
		.amdhsa_user_sgpr_queue_ptr 0
		.amdhsa_user_sgpr_kernarg_segment_ptr 1
		.amdhsa_user_sgpr_dispatch_id 0
		.amdhsa_user_sgpr_kernarg_preload_length 0
		.amdhsa_user_sgpr_kernarg_preload_offset 0
		.amdhsa_user_sgpr_private_segment_size 0
		.amdhsa_uses_dynamic_stack 0
		.amdhsa_enable_private_segment 0
		.amdhsa_system_sgpr_workgroup_id_x 1
		.amdhsa_system_sgpr_workgroup_id_y 0
		.amdhsa_system_sgpr_workgroup_id_z 0
		.amdhsa_system_sgpr_workgroup_info 0
		.amdhsa_system_vgpr_workitem_id 2
		.amdhsa_next_free_vgpr 248
		.amdhsa_next_free_sgpr 102
		.amdhsa_accum_offset 248
		.amdhsa_reserve_vcc 1
		.amdhsa_float_round_mode_32 0
		.amdhsa_float_round_mode_16_64 0
		.amdhsa_float_denorm_mode_32 3
		.amdhsa_float_denorm_mode_16_64 3
		.amdhsa_dx10_clamp 1
		.amdhsa_ieee_mode 1
		.amdhsa_fp16_overflow 0
		.amdhsa_tg_split 0
		.amdhsa_exception_fp_ieee_invalid_op 0
		.amdhsa_exception_fp_denorm_src 0
		.amdhsa_exception_fp_ieee_div_zero 0
		.amdhsa_exception_fp_ieee_overflow 0
		.amdhsa_exception_fp_ieee_underflow 0
		.amdhsa_exception_fp_ieee_inexact 0
		.amdhsa_exception_int_div_zero 0
	.end_amdhsa_kernel

; __global__ void __launch_bounds__(512, 2) fwd_megakernel(Params P) {
amdhsa.kernels:
  - .agpr_count:     0
    .args:
      - .offset:         0
        .size:           120
        .value_kind:     by_value
      - .offset:         120
        .size:           4
        .value_kind:     hidden_block_count_x
      - .offset:         124
        .size:           4
        .value_kind:     hidden_block_count_y
      - .offset:         128
        .size:           4
        .value_kind:     hidden_block_count_z
      - .offset:         132
        .size:           2
        .value_kind:     hidden_group_size_x
      - .offset:         134
        .size:           2
        .value_kind:     hidden_group_size_y
      - .offset:         136
        .size:           2
        .value_kind:     hidden_group_size_z
      - .offset:         138
        .size:           2
        .value_kind:     hidden_remainder_x
      - .offset:         140
        .size:           2
        .value_kind:     hidden_remainder_y
      - .offset:         142
        .size:           2
        .value_kind:     hidden_remainder_z
      - .offset:         160
        .size:           8
        .value_kind:     hidden_global_offset_x
      - .offset:         168
        .size:           8
        .value_kind:     hidden_global_offset_y
      - .offset:         176
        .size:           8
        .value_kind:     hidden_global_offset_z
      - .offset:         184
        .size:           2
        .value_kind:     hidden_grid_dims
      - .offset:         208
        .size:           8
        .value_kind:     hidden_multigrid_sync_arg
      - .offset:         240
        .size:           4
        .value_kind:     hidden_dynamic_lds_size
    .group_segment_fixed_size: 0
    .kernarg_segment_align: 8
    .kernarg_segment_size: 376
    .language:       OpenCL C
    .language_version:
      - 2
      - 0
    .max_flat_workgroup_size: 512
    .name:           _Z14fwd_megakernel6Params
    .private_segment_fixed_size: 0
    .sgpr_count:     108
    .sgpr_spill_count: 215
    .symbol:         _Z14fwd_megakernel6Params.kd
    .uniform_work_group_size: 1
    .uses_dynamic_stack: false
    .vgpr_count:     248
    .vgpr_spill_count: 0
    .wavefront_size: 64
